# first grid barrier via the XCD barrier instead of cooperative-groups sync
# baseline (speedup 1.0000x reference)
.LBB0_93:
	s_load_dwordx2 s[0:1], s[84:85], 0xf8
	s_waitcnt lgkmcnt(0)
	s_cmp_gt_i32 s1, 1
	s_cselect_b64 s[0:1], -1, 0
	s_and_b64 s[0:1], s[36:37], s[0:1]
	s_andn2_b64 vcc, exec, s[0:1]
	s_branch .LBB0_105
	v_lshrrev_b32_e32 v2, 20, v0
	v_lshrrev_b32_e32 v0, 10, v0
	v_or_b32_e32 v0, v0, v2
	s_movk_i32 s0, 0x3ff
	v_and_or_b32 v0, v0, s0, v1
	v_cmp_eq_u32_e32 vcc, 0, v0
	s_barrier
	s_and_saveexec_b64 s[0:1], vcc
	s_cbranch_execz .LBB0_104
	buffer_wbl2 sc1
	s_waitcnt vmcnt(0)
	s_load_dwordx2 s[2:3], s[34:35], 0x58
	v_mov_b32_e32 v2, 0
	s_mov_b64 s[4:5], exec
	v_mbcnt_lo_u32_b32 v1, s4, 0
	v_mbcnt_hi_u32_b32 v1, s5, v1
	s_waitcnt lgkmcnt(0)
	global_load_dword v0, v2, s[2:3] offset:40
	v_cmp_eq_u32_e32 vcc, 0, v1
	s_and_saveexec_b64 s[6:7], vcc
	s_cbranch_execz .LBB0_97
	s_bcnt1_i32_b64 s4, s[4:5]
	v_mov_b32_e32 v3, s4
	global_atomic_add v3, v2, v3, s[2:3] offset:32 sc0

; __global__ void __launch_bounds__(512, 2) mega(Args args) {
;     ...
;     for (int l = 0; l < DEPTH; ++l) {
;         for (int half = 0; half < 2; ++half) {
;             const int L = half ? 2048 : 4096;
;             PH_BEGIN
.LBB0_105:
	v_and_b32_e32 v0, 64, v249
	v_add_u32_e32 v0, 64, v0
	v_xor_b32_e32 v1, 1, v249
	v_cmp_lt_i32_e32 vcc, v1, v0
	s_add_i32 s0, 0, 0x23fc0
	v_writelane_b32 v255, s0, 4
	v_cndmask_b32_e32 v1, v249, v1, vcc
	v_lshlrev_b32_e32 v206, 2, v1
	v_xor_b32_e32 v1, 2, v249
	v_cmp_lt_i32_e32 vcc, v1, v0
	s_add_i32 s0, 0, 0x23fc4
	v_writelane_b32 v255, s0, 5
	v_cndmask_b32_e32 v1, v249, v1, vcc
	v_lshlrev_b32_e32 v207, 2, v1
	v_xor_b32_e32 v1, 4, v249
	v_cmp_lt_i32_e32 vcc, v1, v0
	s_add_i32 s2, 0, 0x8c30
	v_writelane_b32 v255, s2, 6
	v_cndmask_b32_e32 v1, v249, v1, vcc
	v_lshlrev_b32_e32 v208, 2, v1
	v_xor_b32_e32 v1, 8, v249
	v_cmp_lt_i32_e32 vcc, v1, v0
	s_add_i32 s2, 0, 0x19800
	v_writelane_b32 v255, s2, 7
	v_cndmask_b32_e32 v1, v249, v1, vcc
	v_lshlrev_b32_e32 v209, 2, v1
	v_xor_b32_e32 v1, 16, v249
	v_cmp_lt_i32_e32 vcc, v1, v0
	v_writelane_b32 v255, s83, 8
	v_writelane_b32 v255, s84, 9
	v_cndmask_b32_e32 v1, v249, v1, vcc
	v_lshlrev_b32_e32 v210, 2, v1
	v_xor_b32_e32 v1, 32, v249
	v_cmp_lt_i32_e32 vcc, v1, v0
	v_mov_b32_e32 v177, 0
	v_writelane_b32 v255, s85, 10
	v_cndmask_b32_e32 v0, v249, v1, vcc
	v_lshlrev_b32_e32 v211, 2, v0
	v_lshlrev_b32_e32 v0, 2, v249
	s_mov_b32 s75, 1
	v_and_b32_e32 v212, 0x100, v0
	s_mov_b64 s[66:67], 0x200000
	s_mov_b64 s[68:69], 0x80
	s_mov_b32 s70, 0x437f0000
	s_mov_b64 s[72:73], 0x2400
	v_mov_b32_e32 v216, 1
	v_mov_b32_e32 v217, 0x358637bd
	v_mov_b32_e32 v218, 0x3ecc95a3
	s_movk_i32 s0, 0x78
	s_movk_i32 s1, 0x88
	s_mov_b32 s76, 0x3db504f3
	s_add_i32 s82, 0, 0x11000
	s_mov_b32 s43, 0x42b504f3
	s_mov_b32 s78, 0x3e0293ee
	s_mov_b32 s80, 0x3b808081
	v_mov_b32_e32 v221, 0x7f800000
	v_mov_b32_e32 v222, 0x7fc00000
	v_mov_b32_e32 v223, 0xff800000
	v_mov_b32_e32 v224, 0x2200
	v_mov_b32_e32 v225, 0x880
	v_mov_b32_e32 v220, 0x1100
	v_mov_b32_e32 v254, 0x2a80
	v_mov_b32_e32 v219, 0x3300
	v_mov_b32_e32 v214, v177
	v_mov_b32_e32 v215, v177
	s_mov_b32 s79, 0
	s_mov_b32 s45, 0
	v_writelane_b32 v255, s81, 11
	s_mov_b32 s79, -1
	s_mov_b32 s75, 0xffffffeb
	s_branch .Ltramp_a

; #define SBAR() __builtin_amdgcn_sched_barrier(0)
; DI void finishSM(f32x16& p0, f32x16& p1, float alpha, float& l_reg, bf16x8& pa0, bf16x8& pa1, bf16x8& pa2, bf16x8& pa3) {
;   for (int r = 0; r < 16; ++r) p1[r] = __builtin_amdgcn_exp2f(p1[r]);
;   float ps = 0; for (int r = 0; r < 16; ++r) ps += p0[r]; for (int r = 0; r < 16; ++r) ps += p1[r];
;   { auto rr = __builtin_amdgcn_permlane32_swap(__float_as_uint(ps), __float_as_uint(ps), false, false);
;     ps = __uint_as_float(rr[0]) + __uint_as_float(rr[1]); }
;   l_reg = l_reg * alpha + ps;
;     ...
;   PK4(p0, 0, pa0); PK4(p0, 8, pa1); PK4(p1, 0, pa2); PK4(p1, 8, pa3);
;     ...
; }
; DI void qkt(f32x16& p0, f32x16& p1, const bf16_t* Ks, const bf16x8* qr, int r32, int hi) {
;   p0 = f32x16{}; p1 = f32x16{};
;   for (int d0 = 0; d0 < 8; ++d0) { int cb = (d0 * 16 + hi * 8) * 2;
;     bf16x8 b0 = *reinterpret_cast<const bf16x8*>((const char*)Ks + KSWZ(r32, cb));
;     bf16x8 b1 = *reinterpret_cast<const bf16x8*>((const char*)Ks + KSWZ(32 + r32, cb));
;     p0 = __builtin_amdgcn_mfma_f32_32x32x16_bf16(b0, qr[d0], p0, 0, 0, 0);
;     p1 = __builtin_amdgcn_mfma_f32_32x32x16_bf16(b1, qr[d0], p1, 0, 0, 0); }
; }
; DI int v_st(int k, int c) { const int kk = (k & ~0xC) | ((k & 4) << 1) | ((k & 8) >> 1); return ((kk >> 3) * 4 + (c >> 5)) * 512 + ((kk & 7) * 32 + (c & 31)) * 2; }
; DI int v_rd_base(int lane) { return ((lane & 3) << 3) | (((lane >> 2) & 3) << 6) | (((lane >> 4) & 1) << 5) | (((lane >> 5) & 1) << 8); }
; template <int OFF> DI s16x4 tr_read(int vb) {
;   s16x4 r; asm volatile("ds_read_b64_tr_b16 %0, %1 offset:%2" : "=&v"(r) : "v"(vb), "i"(OFF) : "memory"); return r;
; }
; template <int D0> DI void pv_one(f32x16& od, int vb, bf16x8 pa0, bf16x8 pa1, bf16x8 pa2, bf16x8 pa3) {
;   const s16x4 l0 = tr_read<v_rd_off(D0, 0, 0)>(vb), h0 = tr_read<v_rd_off(D0, 0, 1)>(vb), l1 = tr_read<v_rd_off(D0, 1, 0)>(vb), h1 = tr_read<v_rd_off(D0, 1, 1)>(vb);
;   const s16x4 l2 = tr_read<v_rd_off(D0, 2, 0)>(vb), h2 = tr_read<v_rd_off(D0, 2, 1)>(vb), l3 = tr_read<v_rd_off(D0, 3, 0)>(vb), h3 = tr_read<v_rd_off(D0, 3, 1)>(vb);
;   asm volatile("s_waitcnt lgkmcnt(0)" ::: "memory"); SBAR();
;     ...
;   od = __builtin_amdgcn_mfma_f32_32x32x16_bf16(pa0, PK(l0, h0), od, 0, 0, 0);
;   od = __builtin_amdgcn_mfma_f32_32x32x16_bf16(pa1, PK(l1, h1), od, 0, 0, 0);
;   od = __builtin_amdgcn_mfma_f32_32x32x16_bf16(pa2, PK(l2, h2), od, 0, 0, 0);
.LBB0_613:
	v_cndmask_b32_e64 v97, v97, v164, s[4:5]
	v_mul_f32_e32 v97, 0xbe0293ee, v97
	v_fmamk_f32 v80, v80, 0x3e0293ee, v97
	v_fmamk_f32 v81, v81, 0x3e0293ee, v97
	v_fmamk_f32 v106, v93, 0x3e0293ee, v97
	v_fmamk_f32 v93, v74, 0x3e0293ee, v97
	v_exp_f32_e32 v74, v80
	v_fmamk_f32 v82, v82, 0x3e0293ee, v97
	v_fmamk_f32 v107, v94, 0x3e0293ee, v97
	v_fmamk_f32 v94, v75, 0x3e0293ee, v97
	v_exp_f32_e32 v75, v81
	v_fmamk_f32 v83, v83, 0x3e0293ee, v97
	v_fmamk_f32 v110, v95, 0x3e0293ee, v97
	v_fmamk_f32 v95, v76, 0x3e0293ee, v97
	v_exp_f32_e32 v76, v82
	v_fmamk_f32 v84, v84, 0x3e0293ee, v97
	v_fmamk_f32 v64, v64, 0x3e0293ee, v97
	v_exp_f32_e32 v80, v83
	v_fmamk_f32 v98, v85, 0x3e0293ee, v97
	v_fmamk_f32 v99, v86, 0x3e0293ee, v97
	v_fmamk_f32 v100, v87, 0x3e0293ee, v97
	v_fmamk_f32 v101, v88, 0x3e0293ee, v97
	v_fmamk_f32 v102, v89, 0x3e0293ee, v97
	v_fmamk_f32 v103, v90, 0x3e0293ee, v97
	v_fmamk_f32 v104, v91, 0x3e0293ee, v97
	v_fmamk_f32 v105, v92, 0x3e0293ee, v97
	v_fmamk_f32 v65, v65, 0x3e0293ee, v97
	v_fmamk_f32 v85, v66, 0x3e0293ee, v97
	v_fmamk_f32 v86, v67, 0x3e0293ee, v97
	v_fmamk_f32 v87, v68, 0x3e0293ee, v97
	v_fmamk_f32 v88, v69, 0x3e0293ee, v97
	v_fmamk_f32 v89, v70, 0x3e0293ee, v97
	v_fmamk_f32 v90, v71, 0x3e0293ee, v97
	v_fmamk_f32 v91, v72, 0x3e0293ee, v97
	v_fmamk_f32 v92, v73, 0x3e0293ee, v97
	v_exp_f32_e32 v81, v84
	v_fmamk_f32 v77, v77, 0x3e0293ee, v97
	v_fmamk_f32 v78, v78, 0x3e0293ee, v97
	v_fmac_f32_e32 v97, 0x3e0293ee, v79
	v_exp_f32_e32 v79, v64
	v_add_f32_e32 v64, 0, v74
	v_exp_f32_e32 v82, v98
	v_add_f32_e32 v64, v75, v64
	v_exp_f32_e32 v83, v99
	v_add_f32_e32 v64, v76, v64
	v_exp_f32_e32 v84, v100
	v_add_f32_e32 v64, v80, v64
	v_exp_f32_e32 v66, v101
	v_add_f32_e32 v64, v81, v64
	v_exp_f32_e32 v67, v102
	v_add_f32_e32 v64, v82, v64
	v_exp_f32_e32 v68, v103
	v_add_f32_e32 v64, v83, v64
	v_exp_f32_e32 v69, v104
	v_add_f32_e32 v64, v84, v64
	v_exp_f32_e32 v70, v105
	v_add_f32_e32 v64, v66, v64
	v_exp_f32_e32 v71, v106
	v_add_f32_e32 v64, v67, v64
	v_exp_f32_e32 v72, v107
	v_add_f32_e32 v64, v68, v64
	v_exp_f32_e32 v73, v110
	v_add_f32_e32 v64, v69, v64
	v_add_f32_e32 v64, v70, v64
	v_exp_f32_e32 v98, v65
	v_add_f32_e32 v64, v71, v64
	v_exp_f32_e32 v85, v85
	v_add_f32_e32 v64, v72, v64
	v_exp_f32_e32 v86, v86
	v_add_f32_e32 v64, v73, v64
	v_exp_f32_e32 v87, v87
	v_add_f32_e32 v64, v79, v64
	v_exp_f32_e32 v88, v88
	v_add_f32_e32 v64, v98, v64
	v_exp_f32_e32 v89, v89
	v_add_f32_e32 v64, v85, v64
	v_exp_f32_e32 v90, v90
	v_add_f32_e32 v64, v86, v64
	v_exp_f32_e32 v91, v91
	v_add_f32_e32 v64, v87, v64
	v_exp_f32_e32 v92, v92
	v_add_f32_e32 v64, v88, v64
	v_exp_f32_e32 v93, v93
	v_add_f32_e32 v64, v89, v64
	v_exp_f32_e32 v94, v94
	v_add_f32_e32 v64, v90, v64
	v_exp_f32_e32 v95, v95
	v_add_f32_e32 v64, v91, v64
	v_exp_f32_e32 v99, v77
	v_add_f32_e32 v64, v92, v64
	v_exp_f32_e32 v100, v78
	v_add_f32_e32 v64, v93, v64
	v_exp_f32_e32 v97, v97
	v_add_f32_e32 v64, v94, v64
	v_add_f32_e32 v64, v95, v64
	v_add_f32_e32 v64, v99, v64
	v_add_f32_e32 v64, v100, v64
	v_add_f32_e32 v64, v97, v64
	v_mov_b32_e32 v65, v64
	s_nop 1
	v_permlane32_swap_b32_e32 v64, v65
	v_cvt_pk_bf16_f32 v74, v74, v75
	v_cvt_pk_bf16_f32 v75, v76, v80
	v_cvt_pk_bf16_f32 v76, v81, v82
	v_cvt_pk_bf16_f32 v77, v83, v84
	v_cvt_pk_bf16_f32 v66, v66, v67
	v_cvt_pk_bf16_f32 v67, v68, v69
	v_cvt_pk_bf16_f32 v68, v70, v71
	v_cvt_pk_bf16_f32 v69, v72, v73
	v_cvt_pk_bf16_f32 v70, v79, v98
	v_cvt_pk_bf16_f32 v71, v85, v86
	v_cvt_pk_bf16_f32 v72, v87, v88
	v_cvt_pk_bf16_f32 v73, v89, v90
	v_cvt_pk_bf16_f32 v78, v91, v92
	v_cvt_pk_bf16_f32 v79, v93, v94
	v_cvt_pk_bf16_f32 v80, v95, v99
	v_cvt_pk_bf16_f32 v81, v100, v97
	v_permlane32_swap_b32_e32 v74, v76
	v_permlane32_swap_b32_e32 v75, v77
	v_permlane32_swap_b32_e32 v66, v68
	v_permlane32_swap_b32_e32 v67, v69
	v_permlane32_swap_b32_e32 v70, v72
	v_permlane32_swap_b32_e32 v71, v73
	v_permlane32_swap_b32_e32 v78, v80
	v_permlane32_swap_b32_e32 v79, v81
	ds_read_b64_tr_b16 v[82:83], v188 offset:0
	ds_read_b64_tr_b16 v[84:85], v188 offset:0x800
	ds_read_b64_tr_b16 v[86:87], v188 offset:0x1000
	ds_read_b64_tr_b16 v[88:89], v188 offset:0x1800
	ds_read_b64_tr_b16 v[90:91], v188 offset:0x2000
	ds_read_b64_tr_b16 v[92:93], v188 offset:0x2800
	ds_read_b64_tr_b16 v[98:99], v188 offset:0x3000
	ds_read_b64_tr_b16 v[100:101], v188 offset:0x3800
	s_waitcnt lgkmcnt(0)
	s_nop 0
	v_mfma_f32_32x32x16_bf16 v[0:15], v[74:77], v[82:85], v[0:15]
	ds_read_b64_tr_b16 v[82:83], v188 offset:0x200
	ds_read_b64_tr_b16 v[84:85], v188 offset:0xa00
	v_mfma_f32_32x32x16_bf16 v[0:15], v[66:69], v[86:89], v[0:15]
	ds_read_b64_tr_b16 v[86:87], v188 offset:0x1200
	ds_read_b64_tr_b16 v[88:89], v188 offset:0x1a00
	v_mfma_f32_32x32x16_bf16 v[0:15], v[70:73], v[90:93], v[0:15]
	ds_read_b64_tr_b16 v[90:91], v188 offset:0x2200
	ds_read_b64_tr_b16 v[92:93], v188 offset:0x2a00
	ds_read_b64_tr_b16 v[102:103], v188 offset:0x3200
	ds_read_b64_tr_b16 v[104:105], v188 offset:0x3a00
	s_waitcnt lgkmcnt(0)
	v_mfma_f32_32x32x16_bf16 v[0:15], v[78:81], v[98:101], v[0:15]
	v_mfma_f32_32x32x16_bf16 v[48:63], v[74:77], v[82:85], v[48:63]
	ds_read_b64_tr_b16 v[82:83], v188 offset:0x400
	ds_read_b64_tr_b16 v[84:85], v188 offset:0xc00
	v_mfma_f32_32x32x16_bf16 v[48:63], v[66:69], v[86:89], v[48:63]
	ds_read_b64_tr_b16 v[86:87], v188 offset:0x1400
	ds_read_b64_tr_b16 v[88:89], v188 offset:0x1c00
	v_mfma_f32_32x32x16_bf16 v[48:63], v[70:73], v[90:93], v[48:63]
	ds_read_b64_tr_b16 v[90:91], v188 offset:0x2400
	ds_read_b64_tr_b16 v[92:93], v188 offset:0x2c00
	ds_read_b64_tr_b16 v[98:99], v188 offset:0x3400
	ds_read_b64_tr_b16 v[100:101], v188 offset:0x3c00
	s_waitcnt lgkmcnt(0)
	v_mfma_f32_32x32x16_bf16 v[48:63], v[78:81], v[102:105], v[48:63]
	v_mfma_f32_32x32x16_bf16 v[32:47], v[74:77], v[82:85], v[32:47]
	ds_read_b64_tr_b16 v[82:83], v188 offset:0x600
	ds_read_b64_tr_b16 v[84:85], v188 offset:0xe00
	v_mfma_f32_32x32x16_bf16 v[32:47], v[66:69], v[86:89], v[32:47]
	ds_read_b64_tr_b16 v[86:87], v188 offset:0x1600
	ds_read_b64_tr_b16 v[88:89], v188 offset:0x1e00
	v_mfma_f32_32x32x16_bf16 v[32:47], v[70:73], v[90:93], v[32:47]
	ds_read_b64_tr_b16 v[90:91], v188 offset:0x2600
	ds_read_b64_tr_b16 v[92:93], v188 offset:0x2e00
	ds_read_b64_tr_b16 v[102:103], v188 offset:0x3600
	ds_read_b64_tr_b16 v[104:105], v188 offset:0x3e00
	s_waitcnt lgkmcnt(0)
	v_mfma_f32_32x32x16_bf16 v[32:47], v[78:81], v[98:101], v[32:47]
	v_mfma_f32_32x32x16_bf16 v[16:31], v[74:77], v[82:85], v[16:31]
	v_mfma_f32_32x32x16_bf16 v[16:31], v[66:69], v[86:89], v[16:31]
	v_mfma_f32_32x32x16_bf16 v[16:31], v[70:73], v[90:93], v[16:31]
	v_mfma_f32_32x32x16_bf16 v[16:31], v[78:81], v[102:105], v[16:31]
	s_and_saveexec_b64 s[4:5], s[2:3]
	s_cbranch_execz .LBB0_595
	v_add_f32_e32 v66, v108, v109
	v_fmac_f32_e32 v66, v187, v160
	v_add_f32_e32 v64, v64, v65
	v_fmac_f32_e32 v64, v66, v96
	ds_write_b32 v186, v64
	s_branch .LBB0_595
; #define LAS __attribute__((address_space(3)))
; DI void hyena_unit(const Inputs& in, int l, unsigned char* ws, int half, int c, LAS unsigned char* lds, int tid) {
;     const int L = half ? 2048 : 4096, NB = half ? 8 : 4, nblk = L / 32, FRS = half ? FRS1 : FRS0, ZS = L + 2048, ZSP = (ZS / 32) * 40;
;     const bf16_t* FR = (const bf16_t*)(ws + (half ? WS_FR1 : WS_FR0)) + (size_t)c * FRS; const bf16_t* FRO = (const bf16_t*)(ws + (half ? WS_FRO1 : WS_FRO0)) + (size_t)c * FRS;
;     const bf16_t* ZT = (const bf16_t*)(ws + WS_ZT); bf16_t* XT = (bf16_t*)(ws + WS_X0T);
;     constexpr int FRB = 16640;
;     LAS unsigned char* Zl = lds + 2 * FRB;
;     const int cpr = ZS / 8, nfr = (2 * L + 64) / 8;
;     { u32x4 fv[5], zv[8];
; #pragma unroll
;       for (int k = 0; k < 5; ++k) { const int i = tid + 512 * k, cp = i >= nfr, kk = cp ? i - nfr : i; fv[k] = (u32x4){0u, 0u, 0u, 0u};
;           if (i < 2 * nfr && kk < 2 * L / 8) fv[k] = *(const u32x4*)((cp ? FRO : FR) + kk * 8);
;           if (cp && kk == 2 * L / 8 - 1) fv[k].w &= 0xffffu; }
; #pragma unroll
;       for (int k = 0; k < 8; ++k) { const int i = tid + 512 * k, b = i / cpr, j = i % cpr, m = j * 8 - 1024; zv[k] = (u32x4){0u, 0u, 0u, 0u};
;           if (i < NB * cpr && m >= 0 && m < L) zv[k] = *(const u32x4*)(ZT + (size_t)(b * 512 + c) * L + m); }
; #pragma unroll
;       for (int k = 0; k < 5; ++k) { const int i = tid + 512 * k, cp = i >= nfr, kk = cp ? i - nfr : i; if (i < 2 * nfr) *(LAS u32x4*)(lds + cp * FRB + kk * 16) = fv[k]; }
; #pragma unroll
;       for (int k = 0; k < 8; ++k) { const int i = tid + 512 * k, b = i / cpr, j = i % cpr; if (i < NB * cpr) *(LAS u32x4*)(Zl + ((size_t)b * ZSP + (j >> 2) * 40 + (j & 3) * 8) * 2) = zv[k]; } }
.Ltramp_a:
	s_branch .Ltramp_b
.LBB0_615:
	s_cmpk_gt_i32 s79, 0x1ff
	s_cbranch_scc1 .LBB0_674
	s_and_b64 s[2:3], s[90:91], exec
	s_movk_i32 s2, 0x2040
	s_cselect_b32 s44, s2, 0x1040
	s_add_i32 s22, s81, 0x800
	s_lshr_b32 s83, s22, 5
	s_and_b64 s[2:3], s[90:91], exec
	s_mov_b32 s2, 0xc10000
	s_cselect_b32 s6, 0x400000, s2
	s_mov_b32 s2, 0x1dd00000
	s_cselect_b32 s7, s2, 0x1e510000
	s_lshr_b32 s20, s81, 2
	s_or_b32 s42, s20, 8
	v_mov_b32_e32 v0, s42
	v_cmp_le_i32_e32 vcc, s42, v182
	s_lshl_b32 s18, s42, 1
	s_add_i32 s23, s20, -1
	v_cndmask_b32_e32 v1, 0, v0, vcc
	v_sub_u32_e32 v2, v182, v1
	v_cmp_gt_i32_e64 s[2:3], s18, v182
	v_cmp_gt_i32_e64 s[4:5], s20, v2
	s_and_b64 s[46:47], s[2:3], s[4:5]
	v_mov_b32_e32 v1, s6
	v_mov_b32_e32 v3, s7
	v_cmp_eq_u32_e64 s[4:5], s23, v2
	v_add_u32_e32 v4, 0x200, v182
	v_cndmask_b32_e32 v176, v1, v3, vcc
	s_and_b64 s[4:5], vcc, s[4:5]
	v_cmp_le_i32_e32 vcc, s42, v4
	v_cmp_gt_i32_e64 s[6:7], s18, v4
	v_add_u32_e32 v6, 0x400, v182
	v_cndmask_b32_e32 v5, 0, v0, vcc
	v_sub_u32_e32 v5, v4, v5
	v_cmp_gt_i32_e64 s[8:9], s20, v5
	s_and_b64 s[48:49], s[6:7], s[8:9]
	v_cmp_eq_u32_e64 s[8:9], s23, v5
	v_cndmask_b32_e32 v54, v1, v3, vcc
	s_and_b64 s[8:9], vcc, s[8:9]
	v_cmp_le_i32_e32 vcc, s42, v6
	v_cmp_gt_i32_e64 s[10:11], s18, v6
	v_add_u32_e32 v8, 0x600, v182
	v_cndmask_b32_e32 v7, 0, v0, vcc
	v_sub_u32_e32 v7, v6, v7
	v_cmp_gt_i32_e64 s[12:13], s20, v7
	s_and_b64 s[50:51], s[10:11], s[12:13]
	v_cmp_eq_u32_e64 s[12:13], s23, v7
	v_cndmask_b32_e32 v58, v1, v3, vcc
	s_and_b64 s[12:13], vcc, s[12:13]
	v_cmp_le_i32_e32 vcc, s42, v8
	v_cmp_gt_i32_e64 s[14:15], s18, v8
	v_add_u32_e32 v10, 0x800, v182
	v_cndmask_b32_e32 v9, 0, v0, vcc
	v_sub_u32_e32 v9, v8, v9
	v_cmp_gt_i32_e64 s[16:17], s20, v9
	s_and_b64 s[52:53], s[14:15], s[16:17]
	v_cmp_eq_u32_e64 s[16:17], s23, v9
	v_cndmask_b32_e32 v62, v1, v3, vcc
	s_and_b64 s[16:17], vcc, s[16:17]
	v_cmp_le_i32_e32 vcc, s42, v10
	v_cmp_gt_i32_e64 s[18:19], s18, v10
	s_lshr_b32 s89, s81, 5
	v_cndmask_b32_e32 v0, 0, v0, vcc
	v_sub_u32_e32 v11, v10, v0
	v_cmp_gt_i32_e64 s[20:21], s20, v11
	s_and_b64 s[54:55], s[18:19], s[20:21]
	v_cmp_eq_u32_e64 s[20:21], s23, v11
	s_and_b64 s[20:21], vcc, s[20:21]
	s_waitcnt lgkmcnt(0)
	s_add_u32 s74, s92, 0x1bd00000
	s_addc_u32 s75, s93, 0
	s_lshr_b32 s40, s22, 3
	v_cvt_f32_u32_e32 v0, s40
	s_and_b64 s[22:23], s[90:91], exec
	s_cselect_b32 s22, 2, 3
	s_lshl_b32 s41, s40, s22
	v_rcp_iflag_f32_e32 v0, v0
	s_and_b64 s[22:23], s[90:91], exec
	s_cselect_b32 s33, 12, 11
	s_sub_i32 s22, 0, s40
	v_mul_f32_e32 v0, 0x4f7ffffe, v0
	v_cvt_u32_f32_e32 v0, v0
	v_cndmask_b32_e32 v66, v1, v3, vcc
	v_sub_u32_e32 v1, 0, v182
	v_max_i32_e32 v1, v182, v1
	v_mul_lo_u32 v3, s22, v0
	v_mul_hi_u32 v3, v0, v3
	v_add_u32_e32 v3, v0, v3
	v_mul_hi_u32 v0, v1, v3
	v_mul_lo_u32 v12, v0, s40
	v_sub_u32_e32 v1, v1, v12
	v_add_u32_e32 v12, 1, v0
	v_cmp_le_u32_e32 vcc, s40, v1
	v_ashrrev_i32_e32 v22, 31, v182
	v_cmp_gt_i32_e64 s[22:23], s41, v182
	v_cndmask_b32_e32 v0, v0, v12, vcc
	v_subrev_u32_e32 v12, s40, v1
	v_cndmask_b32_e32 v1, v1, v12, vcc
	v_add_u32_e32 v12, 1, v0
	v_cmp_le_u32_e32 vcc, s40, v1
	v_mov_b32_e32 v1, v177
	s_movk_i32 s86, 0x7f
	v_cndmask_b32_e32 v0, v0, v12, vcc
	v_xor_b32_e32 v0, v0, v22
	v_sub_u32_e32 v23, v0, v22
	v_mul_lo_u32 v0, v23, s40
	v_sub_u32_e32 v12, v182, v0
	v_lshlrev_b32_e32 v13, 3, v12
	v_add_u32_e32 v0, 0xfffffc00, v13
	v_lshl_add_u64 v[70:71], v[0:1], 1, s[74:75]
	v_sub_u32_e32 v1, 0, v4
	v_max_i32_e32 v1, v4, v1
	v_mul_hi_u32 v14, v1, v3
	v_cmp_gt_i32_e64 s[24:25], s81, v0
	v_mul_lo_u32 v15, v14, s40
	v_cmp_lt_i32_e32 vcc, s86, v12
	s_and_b64 s[24:25], s[22:23], s[24:25]
	v_sub_u32_e32 v1, v1, v15
	s_and_b64 s[56:57], s[24:25], vcc
	v_add_u32_e32 v15, 1, v14
	v_cmp_le_u32_e32 vcc, s40, v1
	v_ashrrev_i32_e32 v0, 31, v4
	v_cmp_gt_i32_e64 s[24:25], s41, v4
	v_cndmask_b32_e32 v14, v14, v15, vcc
	v_subrev_u32_e32 v15, s40, v1
	v_cndmask_b32_e32 v1, v1, v15, vcc
	v_add_u32_e32 v15, 1, v14
	v_cmp_le_u32_e32 vcc, s40, v1
	v_mov_b32_e32 v47, 0x4140
	v_lshlrev_b32_e32 v52, 3, v2
	v_cndmask_b32_e32 v1, v14, v15, vcc
	v_xor_b32_e32 v1, v1, v0
	v_sub_u32_e32 v24, v1, v0
	v_mul_lo_u32 v0, v24, s40
	v_sub_u32_e32 v14, v4, v0
	v_lshlrev_b32_e32 v15, 3, v14
	v_add_u32_e32 v0, 0xfffffc00, v15
	v_mov_b32_e32 v1, v177
	v_lshl_add_u64 v[72:73], v[0:1], 1, s[74:75]
	v_sub_u32_e32 v1, 0, v6
	v_max_i32_e32 v1, v6, v1
	v_mul_hi_u32 v16, v1, v3
	v_cmp_gt_i32_e64 s[26:27], s81, v0
	v_mul_lo_u32 v17, v16, s40
	v_cmp_lt_i32_e32 vcc, s86, v14
	s_and_b64 s[26:27], s[24:25], s[26:27]
	v_sub_u32_e32 v1, v1, v17
	s_and_b64 s[58:59], s[26:27], vcc
	v_add_u32_e32 v17, 1, v16
	v_cmp_le_u32_e32 vcc, s40, v1
	v_ashrrev_i32_e32 v0, 31, v6
	v_cmp_gt_i32_e64 s[26:27], s41, v6
	v_cndmask_b32_e32 v16, v16, v17, vcc
	v_subrev_u32_e32 v17, s40, v1
	v_cndmask_b32_e32 v1, v1, v17, vcc
	v_add_u32_e32 v17, 1, v16
	v_cmp_le_u32_e32 vcc, s40, v1
	v_lshlrev_b32_e32 v38, 4, v2
	v_and_b32_e32 v2, 24, v15
	v_cndmask_b32_e32 v1, v16, v17, vcc
	v_xor_b32_e32 v1, v1, v0
	v_sub_u32_e32 v25, v1, v0
	v_mul_lo_u32 v0, v25, s40
	v_sub_u32_e32 v16, v6, v0
	v_lshlrev_b32_e32 v17, 3, v16
	v_add_u32_e32 v0, 0xfffffc00, v17
	v_mov_b32_e32 v1, v177
	v_lshl_add_u64 v[74:75], v[0:1], 1, s[74:75]
	v_sub_u32_e32 v1, 0, v8
	v_max_i32_e32 v1, v8, v1
	v_mul_hi_u32 v18, v1, v3
	v_cmp_gt_i32_e64 s[28:29], s81, v0
	v_mul_lo_u32 v19, v18, s40
	v_cmp_lt_i32_e32 vcc, s86, v16
	s_and_b64 s[28:29], s[26:27], s[28:29]
	v_sub_u32_e32 v1, v1, v19
	s_and_b64 s[62:63], s[28:29], vcc
	v_add_u32_e32 v19, 1, v18
	v_cmp_le_u32_e32 vcc, s40, v1
	v_ashrrev_i32_e32 v0, 31, v8
	v_cmp_gt_i32_e64 s[28:29], s41, v8
	v_cndmask_b32_e32 v18, v18, v19, vcc
; #define LAS __attribute__((address_space(3)))
; DI void hyena_unit(const Inputs& in, int l, unsigned char* ws, int half, int c, LAS unsigned char* lds, int tid) {
;     ...
;     { u32x4 fv[5], zv[8];
; #pragma unroll
;       for (int k = 0; k < 5; ++k) { const int i = tid + 512 * k, cp = i >= nfr, kk = cp ? i - nfr : i; fv[k] = (u32x4){0u, 0u, 0u, 0u};
;           if (i < 2 * nfr && kk < 2 * L / 8) fv[k] = *(const u32x4*)((cp ? FRO : FR) + kk * 8);
;           if (cp && kk == 2 * L / 8 - 1) fv[k].w &= 0xffffu; }
; #pragma unroll
;       for (int k = 0; k < 8; ++k) { const int i = tid + 512 * k, b = i / cpr, j = i % cpr, m = j * 8 - 1024; zv[k] = (u32x4){0u, 0u, 0u, 0u};
;           if (i < NB * cpr && m >= 0 && m < L) zv[k] = *(const u32x4*)(ZT + (size_t)(b * 512 + c) * L + m); }
; #pragma unroll
;       for (int k = 0; k < 5; ++k) { const int i = tid + 512 * k, cp = i >= nfr, kk = cp ? i - nfr : i; if (i < 2 * nfr) *(LAS u32x4*)(lds + cp * FRB + kk * 16) = fv[k]; }
; #pragma unroll
;       for (int k = 0; k < 8; ++k) { const int i = tid + 512 * k, b = i / cpr, j = i % cpr; if (i < NB * cpr) *(LAS u32x4*)(Zl + ((size_t)b * ZSP + (j >> 2) * 40 + (j & 3) * 8) * 2) = zv[k]; } }
	v_subrev_u32_e32 v19, s40, v1
	v_cndmask_b32_e32 v1, v1, v19, vcc
	v_add_u32_e32 v19, 1, v18
	v_cmp_le_u32_e32 vcc, s40, v1
	v_lshlrev_b32_e32 v56, 3, v5
	v_lshlrev_b32_e32 v40, 4, v5
	v_cndmask_b32_e32 v1, v18, v19, vcc
	v_xor_b32_e32 v1, v1, v0
	v_sub_u32_e32 v26, v1, v0
	v_mul_lo_u32 v0, v26, s40
	v_sub_u32_e32 v18, v8, v0
	v_lshlrev_b32_e32 v19, 3, v18
	v_add_u32_e32 v0, 0xfffffc00, v19
	v_mov_b32_e32 v1, v177
	v_lshl_add_u64 v[76:77], v[0:1], 1, s[74:75]
	v_sub_u32_e32 v1, 0, v10
	v_max_i32_e32 v1, v10, v1
	v_mul_hi_u32 v20, v1, v3
	v_cmp_gt_i32_e64 s[30:31], s81, v0
	v_mul_lo_u32 v21, v20, s40
	v_cmp_lt_i32_e32 vcc, s86, v18
	s_and_b64 s[30:31], s[28:29], s[30:31]
	v_sub_u32_e32 v1, v1, v21
	s_and_b64 s[94:95], s[30:31], vcc
	v_add_u32_e32 v21, 1, v20
	v_cmp_le_u32_e32 vcc, s40, v1
	v_ashrrev_i32_e32 v0, 31, v10
	v_cmp_gt_i32_e64 s[30:31], s41, v10
	v_cndmask_b32_e32 v20, v20, v21, vcc
	v_subrev_u32_e32 v21, s40, v1
	v_cndmask_b32_e32 v1, v1, v21, vcc
	v_add_u32_e32 v21, 1, v20
	v_cmp_le_u32_e32 vcc, s40, v1
	v_lshlrev_b32_e32 v60, 3, v7
	v_lshlrev_b32_e32 v42, 4, v7
	v_cndmask_b32_e32 v1, v20, v21, vcc
	v_xor_b32_e32 v1, v1, v0
	v_sub_u32_e32 v27, v1, v0
	v_mul_lo_u32 v0, v27, s40
	v_sub_u32_e32 v20, v10, v0
	v_lshlrev_b32_e32 v21, 3, v20
	v_add_u32_e32 v0, 0xfffffc00, v21
	v_mov_b32_e32 v1, v177
	v_lshl_add_u64 v[78:79], v[0:1], 1, s[74:75]
	v_add_u32_e32 v1, 0xa00, v182
	v_sub_u32_e32 v28, 0, v1
	v_max_i32_e32 v28, v1, v28
	v_mul_hi_u32 v29, v28, v3
	v_cmp_gt_i32_e64 s[34:35], s81, v0
	v_mul_lo_u32 v30, v29, s40
	v_cmp_lt_i32_e32 vcc, s86, v20
	s_and_b64 s[34:35], s[30:31], s[34:35]
	v_sub_u32_e32 v28, v28, v30
	s_and_b64 s[96:97], s[34:35], vcc
	v_add_u32_e32 v30, 1, v29
	v_cmp_le_u32_e32 vcc, s40, v28
	v_ashrrev_i32_e32 v0, 31, v1
	v_cmp_gt_i32_e64 s[34:35], s41, v1
	v_cndmask_b32_e32 v29, v29, v30, vcc
	v_subrev_u32_e32 v30, s40, v28
	v_cndmask_b32_e32 v28, v28, v30, vcc
	v_add_u32_e32 v30, 1, v29
	v_cmp_le_u32_e32 vcc, s40, v28
	v_lshlrev_b32_e32 v64, 3, v9
	v_lshlrev_b32_e32 v44, 4, v9
	v_cndmask_b32_e32 v28, v29, v30, vcc
	v_xor_b32_e32 v28, v28, v0
	v_sub_u32_e32 v28, v28, v0
	v_mul_lo_u32 v0, v28, s40
	v_sub_u32_e32 v29, v1, v0
	v_lshlrev_b32_e32 v30, 3, v29
	v_add_u32_e32 v0, 0xfffffc00, v30
	v_mov_b32_e32 v1, v177
	v_lshl_add_u64 v[80:81], v[0:1], 1, s[74:75]
	v_add_u32_e32 v1, 0xc00, v182
	v_sub_u32_e32 v31, 0, v1
	v_max_i32_e32 v31, v1, v31
	v_mul_hi_u32 v32, v31, v3
	v_cmp_gt_i32_e64 s[36:37], s81, v0
	v_mul_lo_u32 v33, v32, s40
	v_cmp_lt_i32_e32 vcc, s86, v29
	s_and_b64 s[36:37], s[34:35], s[36:37]
	v_sub_u32_e32 v31, v31, v33
	s_and_b64 s[64:65], s[36:37], vcc
	v_add_u32_e32 v33, 1, v32
	v_cmp_le_u32_e32 vcc, s40, v31
	v_ashrrev_i32_e32 v0, 31, v1
	v_cmp_gt_i32_e64 s[36:37], s41, v1
	v_cndmask_b32_e32 v32, v32, v33, vcc
	v_subrev_u32_e32 v33, s40, v31
	v_cndmask_b32_e32 v31, v31, v33, vcc
	v_add_u32_e32 v33, 1, v32
	v_cmp_le_u32_e32 vcc, s40, v31
	v_lshlrev_b32_e32 v68, 3, v11
	v_lshlrev_b32_e32 v46, 4, v11
	v_cndmask_b32_e32 v31, v32, v33, vcc
	v_xor_b32_e32 v31, v31, v0
	v_sub_u32_e32 v31, v31, v0
	v_mul_lo_u32 v0, v31, s40
	v_sub_u32_e32 v32, v1, v0
	v_lshlrev_b32_e32 v33, 3, v32
	v_add_u32_e32 v0, 0xfffffc00, v33
	v_mov_b32_e32 v1, v177
	v_lshl_add_u64 v[82:83], v[0:1], 1, s[74:75]
	v_add_u32_e32 v1, 0xe00, v182
	v_sub_u32_e32 v34, 0, v1
	v_max_i32_e32 v34, v1, v34
	v_mul_hi_u32 v3, v34, v3
	v_cmp_gt_i32_e64 s[38:39], s81, v0
	v_mul_lo_u32 v35, v3, s40
	v_cmp_lt_i32_e32 vcc, s86, v32
	s_and_b64 s[38:39], s[36:37], s[38:39]
	v_sub_u32_e32 v34, v34, v35
	s_and_b64 s[84:85], s[38:39], vcc
	v_add_u32_e32 v35, 1, v3
	v_cmp_le_u32_e32 vcc, s40, v34
	v_ashrrev_i32_e32 v0, 31, v1
	v_cmp_gt_i32_e64 s[38:39], s41, v1
	v_cndmask_b32_e32 v3, v3, v35, vcc
	v_subrev_u32_e32 v35, s40, v34
	v_cndmask_b32_e32 v34, v34, v35, vcc
	v_add_u32_e32 v35, 1, v3
	v_cmp_le_u32_e32 vcc, s40, v34
	s_mul_i32 s88, s83, 0x50
	v_ashrrev_i32_e32 v53, 31, v52
	v_cndmask_b32_e32 v3, v3, v35, vcc
	v_xor_b32_e32 v3, v3, v0
	v_sub_u32_e32 v34, v3, v0
	v_mul_lo_u32 v0, v34, s40
	v_sub_u32_e32 v35, v1, v0
	v_lshlrev_b32_e32 v36, 3, v35
	v_add_u32_e32 v0, 0xfffffc00, v36
	v_cmp_gt_i32_e64 s[40:41], s81, v0
	v_cmp_lt_i32_e32 vcc, s86, v35
	s_and_b64 s[40:41], s[38:39], s[40:41]
	s_and_b64 s[86:87], s[40:41], vcc
	v_mov_b32_e32 v1, v177
	v_cmp_gt_i32_e32 vcc, s42, v182
	v_lshl_add_u64 v[84:85], v[0:1], 1, s[74:75]
	v_lshrrev_b32_e32 v1, 2, v12
	v_cndmask_b32_e64 v0, v47, 0, vcc
	v_cmp_gt_i32_e32 vcc, s42, v4
	v_add_u32_e32 v37, 0, v0
	v_and_b32_e32 v4, 24, v17
	v_cndmask_b32_e64 v0, v47, 0, vcc
	v_cmp_gt_i32_e32 vcc, s42, v6
	v_add_u32_e32 v39, 0, v0
	v_and_b32_e32 v6, 24, v19
	v_cndmask_b32_e64 v0, v47, 0, vcc
	v_cmp_gt_i32_e32 vcc, s42, v8
; #define LAS __attribute__((address_space(3)))
; DI void hyena_unit(const Inputs& in, int l, unsigned char* ws, int half, int c, LAS unsigned char* lds, int tid) {
;     ...
;       for (int k = 0; k < 8; ++k) { const int i = tid + 512 * k, b = i / cpr, j = i % cpr, m = j * 8 - 1024; zv[k] = (u32x4){0u, 0u, 0u, 0u};
;           if (i < NB * cpr && m >= 0 && m < L) zv[k] = *(const u32x4*)(ZT + (size_t)(b * 512 + c) * L + m); }
; #pragma unroll
;       for (int k = 0; k < 5; ++k) { const int i = tid + 512 * k, cp = i >= nfr, kk = cp ? i - nfr : i; if (i < 2 * nfr) *(LAS u32x4*)(lds + cp * FRB + kk * 16) = fv[k]; }
; #pragma unroll
;       for (int k = 0; k < 8; ++k) { const int i = tid + 512 * k, b = i / cpr, j = i % cpr; if (i < NB * cpr) *(LAS u32x4*)(Zl + ((size_t)b * ZSP + (j >> 2) * 40 + (j & 3) * 8) * 2) = zv[k]; } }
;     __syncthreads();
;     const int wave = tid >> 6, lane = tid & 63, i32 = lane & 31, g = lane >> 5;
;     const int gpb = nblk / 32, a0 = 32 * (wave % gpb), b0 = 2 * (wave / gpb);
;     const int dlo = a0 - nblk + 1, dhi = a0 + 31;
;     f32x16 acc0 = {}, acc1 = {};
;     const LAS unsigned char* Zb = Zl + (size_t)b0 * ZSP * 2;
;     const int zstep = ZSP * 2;
;     int s0 = L - 32 * dlo - i32 + 8 * g;
;     const LAS unsigned char* zp0 = Zb + ((32 + a0 + i32 - dlo) * 40 + 8 * g) * 2;
	v_add_u32_e32 v41, 0, v0
	s_lshr_b32 s74, s81, 10
	v_cndmask_b32_e64 v0, v47, 0, vcc
	v_cmp_gt_i32_e32 vcc, s42, v10
	v_add_u32_e32 v43, 0, v0
	v_and_b32_e32 v8, 24, v21
	v_cndmask_b32_e64 v0, v47, 0, vcc
	v_add_u32_e32 v45, 0, v0
	v_and_b32_e32 v0, 24, v13
	v_mad_u64_u32 v[0:1], s[40:41], v1, 40, v[0:1]
	v_lshrrev_b32_e32 v1, 2, v14
	v_mad_u64_u32 v[2:3], s[40:41], v1, 40, v[2:3]
	v_lshrrev_b32_e32 v1, 2, v16
	v_mad_u64_u32 v[4:5], s[40:41], v1, 40, v[4:5]
	v_lshrrev_b32_e32 v1, 2, v18
	v_mad_u64_u32 v[6:7], s[40:41], v1, 40, v[6:7]
	v_lshrrev_b32_e32 v1, 2, v20
	v_cvt_f32_u32_e32 v3, s74
	v_mad_u64_u32 v[8:9], s[40:41], v1, 40, v[8:9]
	v_lshrrev_b32_e32 v1, 2, v29
	v_and_b32_e32 v10, 24, v30
	v_mad_u64_u32 v[10:11], s[40:41], v1, 40, v[10:11]
	v_lshrrev_b32_e32 v1, 2, v32
	v_and_b32_e32 v12, 24, v33
	v_mad_u64_u32 v[12:13], s[40:41], v1, 40, v[12:13]
	v_lshrrev_b32_e32 v1, 2, v35
	v_and_b32_e32 v14, 24, v36
	v_mad_u64_u32 v[14:15], s[40:41], v1, 40, v[14:15]
	v_rcp_iflag_f32_e32 v1, v3
	s_sub_i32 s40, 0, s74
	v_ashrrev_i32_e32 v3, 6, v182
	v_sub_u32_e32 v9, 0, v3
	v_mul_f32_e32 v1, 0x4f7ffffe, v1
	v_cvt_u32_f32_e32 v1, v1
	v_max_i32_e32 v9, v3, v9
	v_and_b32_e32 v5, 31, v182
	v_bfe_u32 v7, v182, 5, 1
	v_mul_lo_u32 v11, s40, v1
	v_mul_hi_u32 v11, v1, v11
	v_add_u32_e32 v1, v1, v11
	v_mul_hi_u32 v1, v9, v1
	v_mul_lo_u32 v11, v1, s74
	v_sub_u32_e32 v9, v9, v11
	v_add_u32_e32 v11, 1, v1
	v_cmp_le_u32_e32 vcc, s74, v9
	s_mul_i32 s40, s83, 0xa0
	s_mul_i32 s42, s83, 40
	v_cndmask_b32_e32 v1, v1, v11, vcc
	v_subrev_u32_e32 v11, s74, v9
	v_cndmask_b32_e32 v9, v9, v11, vcc
	v_add_u32_e32 v11, 1, v1
	v_cmp_le_u32_e32 vcc, s74, v9
	v_mov_b32_e32 v17, v177
	v_mov_b32_e32 v55, v177
	v_cndmask_b32_e32 v1, v1, v11, vcc
	v_xor_b32_e32 v1, v1, v22
	v_sub_u32_e32 v9, v1, v22
	v_mul_lo_u32 v11, v9, s74
	v_sub_u32_e32 v13, v3, v11
	v_lshlrev_b32_e32 v13, 5, v13
	v_subrev_u32_e32 v15, s89, v13
	v_or_b32_e32 v16, 31, v13
	v_mul_lo_u32 v29, s40, v9
	v_cmp_lt_i32_e64 s[40:41], v15, v16
	v_and_b32_e32 v15, 1, v182
	v_cmp_eq_u32_e32 vcc, 1, v15
	v_or_b32_e32 v13, v13, v5
	v_lshlrev_b32_e32 v92, 10, v9
	v_cndmask_b32_e32 v15, 0, v47, vcc
	v_add_u32_e32 v91, 0, v15
	v_lshlrev_b32_e32 v15, 2, v7
	v_mul_lo_u32 v9, v13, 40
	v_lshlrev_b32_e32 v18, 5, v13
	v_or_b32_e32 v9, v9, v15
	v_mov_b32_e32 v13, 0xa00
	v_lshl_add_u32 v94, v9, 1, v13
	v_mul_lo_u32 v13, v23, s42
	v_lshlrev_b32_e32 v16, 3, v7
	v_add_lshl_u32 v0, v0, v13, 1
	v_mul_lo_u32 v13, v24, s42
	s_add_u32 s74, s92, 0x1cd00000
	v_add_lshl_u32 v2, v2, v13, 1
	v_mul_lo_u32 v13, v25, s42
	v_lshl_or_b32 v11, v11, 10, v16
	s_addc_u32 s75, s93, 0
	v_ashrrev_i32_e32 v19, 31, v18
	v_add_lshl_u32 v4, v4, v13, 1
	v_mul_lo_u32 v13, v26, s42
	v_lshl_add_u32 v11, s81, 1, v11
	v_lshl_add_u64 v[20:21], v[18:19], 1, s[74:75]
	v_or_b32_e32 v18, v18, v15
	v_add_lshl_u32 v6, v6, v13, 1
	v_mul_lo_u32 v13, v27, s42
	v_sub_u32_e32 v11, v11, v5
	v_lshlrev_b32_e32 v3, 10, v3
	v_ashrrev_i32_e32 v19, 31, v18
	v_add_lshl_u32 v8, v8, v13, 1
	v_mul_lo_u32 v13, v28, s42
	v_sub_u32_e32 v3, v11, v3
	v_add_lshl_u32 v10, v10, v13, 1
	v_mul_lo_u32 v13, v31, s42
	v_lshl_add_u64 v[88:89], v[18:19], 1, s[74:75]
	v_add_u32_e32 v103, -16, v3
	v_add_u32_e32 v3, s89, v5
	s_movk_i32 s74, 0x50
	v_add_lshl_u32 v12, v12, v13, 1
	v_mul_lo_u32 v13, v34, s42
	v_mad_u32_u24 v5, v3, s74, v29
	v_lshlrev_b32_e32 v7, 4, v7
	v_readlane_b32 s75, v255, 6
	s_movk_i32 s42, 0xa0
	v_mul_lo_u32 v1, v1, s42
	v_add3_u32 v104, v5, v7, s75
	v_mul_i32_i24_e32 v5, 0xa0, v22
	v_sub_u32_e32 v1, v1, v5
	v_add_u32_e32 v1, 0x50, v1
	v_add_u32_e32 v90, 0, v29
	v_mul_lo_u32 v1, s83, v1
	v_add_u32_e32 v9, s88, v90
	v_add_lshl_u32 v13, v14, v13, 1
	v_mad_u32_u24 v1, v3, s74, v1
	s_mul_i32 s81, s89, 0x50
	v_ashrrev_i32_e32 v57, 31, v56
	v_mov_b32_e32 v59, v177
	v_ashrrev_i32_e32 v61, 31, v60
	v_mov_b32_e32 v63, v177
	v_ashrrev_i32_e32 v65, 31, v64
	v_mov_b32_e32 v67, v177
	v_ashrrev_i32_e32 v69, 31, v68
	v_lshl_add_u64 v[86:87], v[20:21], 0, v[16:17]
	v_or_b32_e32 v93, 0x200, v92
	v_lshlrev_b32_e32 v95, 9, v23
	v_lshlrev_b32_e32 v96, 9, v24
	v_lshlrev_b32_e32 v97, 9, v25
	v_lshlrev_b32_e32 v98, 9, v26
	v_lshlrev_b32_e32 v99, 9, v27
	v_lshlrev_b32_e32 v100, 9, v28
	v_lshlrev_b32_e32 v101, 9, v31
	v_lshlrev_b32_e32 v102, 9, v34
	v_add3_u32 v105, v1, v7, s75
	s_addk_i32 s81, 0x9b0
	v_add_u32_e32 v106, v37, v38
	v_add_u32_e32 v107, v39, v40
	v_add_u32_e32 v108, v41, v42
	v_add_u32_e32 v109, v43, v44
	v_add_u32_e32 v110, v45, v46
	v_add_u32_e32 v111, 0, v0
	v_add_u32_e32 v112, 0, v2
	v_add_u32_e32 v113, 0, v4
	v_add_u32_e32 v114, 0, v6
	v_add_u32_e32 v115, 0, v8
	v_add_u32_e32 v116, 0, v10
	v_add_u32_e32 v117, 0, v12
	v_add_u32_e32 v118, 0, v13
	v_add_u32_e32 v119, v9, v94
	s_branch .LBB0_618

; #define LDS_WAIT() asm volatile("s_waitcnt lgkmcnt(0)" ::: "memory")
; DI u32x4 pack8(f32x4 a, f32x4 b) { u32x4 w; w.x = cvt_pk_bf16(a[0], a[1]); w.y = cvt_pk_bf16(a[2], a[3]); w.z = cvt_pk_bf16(b[0], b[1]); w.w = cvt_pk_bf16(b[2], b[3]); return w; }
;     DI void operator()(f32x4 (&acc)[2][2][4][2], const Unit& u, int wr, int wc, int fr, int fq, LAS unsigned char* lx) const {
;     ...
;         LDS_WAIT(); __builtin_amdgcn_s_barrier(); asm volatile("" ::: "memory");
; #pragma unroll
;         for (int ai = 0; ai < 2; ++ai)
; #pragma unroll
;             for (int m = 0; m < 4; ++m) {
;                 const int r = ai * HALF + wr * 64 + m * 16 + fr;
;                 const f32x2 a = X[r * 4 + 0], b = X[r * 4 + 1], c = X[r * 4 + 2], d = X[r * 4 + 3];
;                 const float M = fmaxf(fmaxf(a.x, b.x), fmaxf(c.x, d.x));
;                 const float S = a.y * __expf(a.x - M) + b.y * __expf(b.x - M) + c.y * __expf(c.x - M) + d.y * __expf(d.x - M);
;                 const float fac = __expf(X[r * 4 + wc].x - M) / S;
;                 bf16_t* rowp = O + (size_t)(u.pm * BM + r) * ldc + u.z * 256 + wc * 32 + 8 * fq;
; #pragma unroll
;                 for (int bj = 0; bj < 2; ++bj) *(u32x4*)(rowp + bj * HALF) = pack8(acc[ai][bj][m][0] * fac, acc[ai][bj][m][1] * fac);
;                 __builtin_amdgcn_sched_barrier(0);
;             }
.LBB0_1156:
	s_or_b64 exec, exec, s[18:19]
	s_waitcnt lgkmcnt(0)
	v_add_u32_e32 v136, s52, v143
	s_add_i32 s18, 0, 0x20000
	s_waitcnt lgkmcnt(0)
	s_barrier
	v_lshl_add_u32 v137, v136, 5, s18
	v_lshlrev_b32_e32 v64, 3, v142
	ds_read_b128 v[142:145], v137
	ds_read_b128 v[146:149], v137 offset:16
	v_add_u32_e32 v137, s55, v137
	s_lshl_b32 s9, s16, 8
	s_lshl_b32 s16, s59, 8
	s_ashr_i32 s17, s16, 31
	s_waitcnt lgkmcnt(0)
	v_max_f32_e32 v150, v148, v148
	v_max_f32_e32 v151, v146, v146
	v_max_f32_e32 v150, v151, v150
	v_max3_f32 v152, v142, v144, v150
	v_sub_f32_e32 v142, v142, v152
	v_mul_f32_e32 v142, 0x3fb8aa3b, v142
	v_exp_f32_e32 v150, v142
	v_sub_f32_e32 v142, v144, v152
	v_mul_f32_e32 v142, 0x3fb8aa3b, v142
	v_exp_f32_e32 v151, v142
	v_mov_b32_e32 v144, v143
	s_lshl_b64 s[16:17], s[16:17], 1
	v_ashrrev_i32_e32 v65, 31, v64
	v_pk_mul_f32 v[142:143], v[144:145], v[150:151]
	v_sub_f32_e32 v144, v146, v152
	v_mul_f32_e32 v144, 0x3fb8aa3b, v144
	v_exp_f32_e32 v145, v144
	v_sub_f32_e32 v144, v148, v152
	v_mul_f32_e32 v144, 0x3fb8aa3b, v144
	v_exp_f32_e32 v144, v144
	v_mov_b32_e32 v146, v149
	v_add_f32_e32 v142, v142, v143
	v_lshlrev_b64 v[64:65], 1, v[64:65]
	v_pk_mul_f32 v[144:145], v[146:147], v[144:145]
	s_nop 0
	v_add_f32_e32 v142, v145, v142
	v_add_f32_e32 v144, v144, v142
	s_waitcnt vmcnt(0)
	ds_read_b64 v[142:143], v137
	s_waitcnt lgkmcnt(0)
	v_sub_f32_e32 v137, v142, v152
	v_mul_f32_e32 v137, 0x3fb8aa3b, v137
	v_exp_f32_e32 v137, v137
	s_nop 0
	v_div_scale_f32 v142, s[20:21], v144, v144, v137
	v_rcp_f32_e32 v143, v142
	s_nop 0
	v_fma_f32 v145, -v142, v143, 1.0
	v_fmac_f32_e32 v143, v145, v143
	v_div_scale_f32 v145, vcc, v137, v144, v137
	v_mul_f32_e32 v146, v145, v143
	v_fma_f32 v147, -v142, v146, v145
	v_fmac_f32_e32 v146, v147, v143
	v_fma_f32 v142, -v142, v146, v145
	v_div_fmas_f32 v142, v142, v143, v146
	v_div_fixup_f32 v142, v142, v144, v137
	v_add_u32_e32 v144, s9, v136
	v_ashrrev_i32_e32 v145, 31, v144
	v_lshlrev_b64 v[144:145], 11, v[144:145]
	v_lshl_add_u64 v[144:145], s[4:5], 0, v[144:145]
	v_lshl_add_u64 v[144:145], v[144:145], 0, s[16:17]
	v_lshl_add_u64 v[144:145], v[144:145], 0, s[44:45]
	v_pk_mul_f32 v[126:127], v[126:127], v[142:143] op_sel_hi:[1,0]
	v_pk_mul_f32 v[124:125], v[124:125], v[142:143] op_sel_hi:[1,0]
	v_pk_mul_f32 v[146:147], v[122:123], v[142:143] op_sel_hi:[1,0]
	v_pk_mul_f32 v[122:123], v[120:121], v[142:143] op_sel_hi:[1,0]
	v_lshl_add_u64 v[144:145], v[144:145], 0, v[64:65]
	v_cvt_pk_bf16_f32 v120, v124, v125
	v_cvt_pk_bf16_f32 v121, v126, v127
	v_cvt_pk_bf16_f32 v122, v122, v123
	v_cvt_pk_bf16_f32 v123, v146, v147
	global_store_dwordx4 v[144:145], v[120:123], off
	v_pk_mul_f32 v[118:119], v[118:119], v[142:143] op_sel_hi:[1,0]
	v_pk_mul_f32 v[116:117], v[116:117], v[142:143] op_sel_hi:[1,0]
	v_pk_mul_f32 v[120:121], v[114:115], v[142:143] op_sel_hi:[1,0]
	v_pk_mul_f32 v[122:123], v[134:135], v[142:143] op_sel_hi:[1,0]
	v_cvt_pk_bf16_f32 v114, v116, v117
	v_cvt_pk_bf16_f32 v115, v118, v119
	v_cvt_pk_bf16_f32 v116, v122, v123
	v_cvt_pk_bf16_f32 v117, v120, v121
	global_store_dwordx4 v[144:145], v[114:117], off offset:256
	v_add_u32_e32 v124, 16, v136
	v_lshl_add_u32 v125, v124, 5, s18
	ds_read_b128 v[114:117], v125
	ds_read_b128 v[118:121], v125 offset:16
	s_waitcnt lgkmcnt(0)
	v_max_f32_e32 v122, v120, v120
	v_max_f32_e32 v123, v118, v118
	v_max_f32_e32 v122, v123, v122
	v_max3_f32 v126, v114, v116, v122
	v_sub_f32_e32 v114, v114, v126
	v_mul_f32_e32 v114, 0x3fb8aa3b, v114
	v_exp_f32_e32 v122, v114
	v_sub_f32_e32 v114, v116, v126
	v_mul_f32_e32 v114, 0x3fb8aa3b, v114
	v_exp_f32_e32 v123, v114
	v_mov_b32_e32 v116, v115
	v_pk_mul_f32 v[114:115], v[116:117], v[122:123]
	v_sub_f32_e32 v116, v118, v126
	v_mul_f32_e32 v116, 0x3fb8aa3b, v116
	v_exp_f32_e32 v117, v116
	v_sub_f32_e32 v116, v120, v126
	v_mul_f32_e32 v116, 0x3fb8aa3b, v116
	v_exp_f32_e32 v116, v116
	v_mov_b32_e32 v118, v121
	v_add_f32_e32 v114, v114, v115
	v_pk_mul_f32 v[116:117], v[118:119], v[116:117]
	s_nop 0
	v_add_f32_e32 v114, v117, v114
	v_add_f32_e32 v116, v116, v114
	v_add_u32_e32 v114, s55, v125
	ds_read_b64 v[114:115], v114
	s_waitcnt lgkmcnt(0)
	v_sub_f32_e32 v114, v114, v126
	v_mul_f32_e32 v114, 0x3fb8aa3b, v114
	v_exp_f32_e32 v114, v114
	s_nop 0
	v_div_scale_f32 v115, s[20:21], v116, v116, v114
	v_rcp_f32_e32 v117, v115
	s_nop 0
	v_fma_f32 v118, -v115, v117, 1.0
	v_fmac_f32_e32 v117, v118, v117
	v_div_scale_f32 v118, vcc, v114, v116, v114
	v_mul_f32_e32 v119, v118, v117
	v_fma_f32 v120, -v115, v119, v118
	v_fmac_f32_e32 v119, v120, v117
	v_fma_f32 v115, -v115, v119, v118
	v_div_fmas_f32 v115, v115, v117, v119
	v_div_fixup_f32 v114, v115, v116, v114
	v_add_u32_e32 v116, s9, v124
	v_ashrrev_i32_e32 v117, 31, v116
	v_lshlrev_b64 v[116:117], 11, v[116:117]
	v_lshl_add_u64 v[116:117], s[4:5], 0, v[116:117]
	v_lshl_add_u64 v[116:117], v[116:117], 0, s[16:17]
	v_lshl_add_u64 v[116:117], v[116:117], 0, s[44:45]
	v_pk_mul_f32 v[110:111], v[110:111], v[114:115] op_sel_hi:[1,0]
	v_pk_mul_f32 v[108:109], v[108:109], v[114:115] op_sel_hi:[1,0]
	v_pk_mul_f32 v[118:119], v[106:107], v[114:115] op_sel_hi:[1,0]
	v_pk_mul_f32 v[106:107], v[104:105], v[114:115] op_sel_hi:[1,0]
	v_lshl_add_u64 v[116:117], v[116:117], 0, v[64:65]
	v_cvt_pk_bf16_f32 v104, v108, v109
	v_cvt_pk_bf16_f32 v105, v110, v111
	v_cvt_pk_bf16_f32 v106, v106, v107
	v_cvt_pk_bf16_f32 v107, v118, v119
	global_store_dwordx4 v[116:117], v[104:107], off
	v_pk_mul_f32 v[102:103], v[102:103], v[114:115] op_sel_hi:[1,0]
	v_pk_mul_f32 v[100:101], v[100:101], v[114:115] op_sel_hi:[1,0]
	v_pk_mul_f32 v[104:105], v[98:99], v[114:115] op_sel_hi:[1,0]
	v_pk_mul_f32 v[106:107], v[112:113], v[114:115] op_sel_hi:[1,0]
	v_cvt_pk_bf16_f32 v98, v100, v101
	v_cvt_pk_bf16_f32 v99, v102, v103
	v_cvt_pk_bf16_f32 v100, v106, v107
	v_cvt_pk_bf16_f32 v101, v104, v105
	global_store_dwordx4 v[116:117], v[98:101], off offset:256
	v_add_u32_e32 v108, 32, v136
	v_lshl_add_u32 v109, v108, 5, s18
	ds_read_b128 v[98:101], v109
	ds_read_b128 v[102:105], v109 offset:16
	s_waitcnt lgkmcnt(0)
; DI u32x4 pack8(f32x4 a, f32x4 b) { u32x4 w; w.x = cvt_pk_bf16(a[0], a[1]); w.y = cvt_pk_bf16(a[2], a[3]); w.z = cvt_pk_bf16(b[0], b[1]); w.w = cvt_pk_bf16(b[2], b[3]); return w; }
;     DI void operator()(f32x4 (&acc)[2][2][4][2], const Unit& u, int wr, int wc, int fr, int fq, LAS unsigned char* lx) const {
;     ...
;         for (int ai = 0; ai < 2; ++ai)
; #pragma unroll
;             for (int m = 0; m < 4; ++m) {
;                 const int r = ai * HALF + wr * 64 + m * 16 + fr;
;                 const f32x2 a = X[r * 4 + 0], b = X[r * 4 + 1], c = X[r * 4 + 2], d = X[r * 4 + 3];
;                 const float M = fmaxf(fmaxf(a.x, b.x), fmaxf(c.x, d.x));
;                 const float S = a.y * __expf(a.x - M) + b.y * __expf(b.x - M) + c.y * __expf(c.x - M) + d.y * __expf(d.x - M);
;                 const float fac = __expf(X[r * 4 + wc].x - M) / S;
;                 bf16_t* rowp = O + (size_t)(u.pm * BM + r) * ldc + u.z * 256 + wc * 32 + 8 * fq;
; #pragma unroll
;                 for (int bj = 0; bj < 2; ++bj) *(u32x4*)(rowp + bj * HALF) = pack8(acc[ai][bj][m][0] * fac, acc[ai][bj][m][1] * fac);
;                 __builtin_amdgcn_sched_barrier(0);
;             }
	v_max_f32_e32 v106, v104, v104
	v_max_f32_e32 v107, v102, v102
	v_max_f32_e32 v106, v107, v106
	v_max3_f32 v110, v98, v100, v106
	v_sub_f32_e32 v98, v98, v110
	v_mul_f32_e32 v98, 0x3fb8aa3b, v98
	v_exp_f32_e32 v106, v98
	v_sub_f32_e32 v98, v100, v110
	v_mul_f32_e32 v98, 0x3fb8aa3b, v98
	v_exp_f32_e32 v107, v98
	v_mov_b32_e32 v100, v99
	v_pk_mul_f32 v[98:99], v[100:101], v[106:107]
	v_sub_f32_e32 v100, v102, v110
	v_mul_f32_e32 v100, 0x3fb8aa3b, v100
	v_exp_f32_e32 v101, v100
	v_sub_f32_e32 v100, v104, v110
	v_mul_f32_e32 v100, 0x3fb8aa3b, v100
	v_exp_f32_e32 v100, v100
	v_mov_b32_e32 v102, v105
	v_add_f32_e32 v98, v98, v99
	v_pk_mul_f32 v[100:101], v[102:103], v[100:101]
	s_nop 0
	v_add_f32_e32 v98, v101, v98
	v_add_f32_e32 v100, v100, v98
	v_add_u32_e32 v98, s55, v109
	ds_read_b64 v[98:99], v98
	s_waitcnt lgkmcnt(0)
	v_sub_f32_e32 v98, v98, v110
	v_mul_f32_e32 v98, 0x3fb8aa3b, v98
	v_exp_f32_e32 v98, v98
	s_nop 0
	v_div_scale_f32 v99, s[20:21], v100, v100, v98
	v_rcp_f32_e32 v101, v99
	s_nop 0
	v_fma_f32 v102, -v99, v101, 1.0
	v_fmac_f32_e32 v101, v102, v101
	v_div_scale_f32 v102, vcc, v98, v100, v98
	v_mul_f32_e32 v103, v102, v101
	v_fma_f32 v104, -v99, v103, v102
	v_fmac_f32_e32 v103, v104, v101
	v_fma_f32 v99, -v99, v103, v102
	v_div_fmas_f32 v99, v99, v101, v103
	v_div_fixup_f32 v98, v99, v100, v98
	v_add_u32_e32 v100, s9, v108
	v_ashrrev_i32_e32 v101, 31, v100
	v_lshlrev_b64 v[100:101], 11, v[100:101]
	v_lshl_add_u64 v[100:101], s[4:5], 0, v[100:101]
	v_lshl_add_u64 v[100:101], v[100:101], 0, s[16:17]
	v_lshl_add_u64 v[100:101], v[100:101], 0, s[44:45]
	v_pk_mul_f32 v[94:95], v[94:95], v[98:99] op_sel_hi:[1,0]
	v_pk_mul_f32 v[92:93], v[92:93], v[98:99] op_sel_hi:[1,0]
	v_pk_mul_f32 v[102:103], v[90:91], v[98:99] op_sel_hi:[1,0]
	v_pk_mul_f32 v[90:91], v[88:89], v[98:99] op_sel_hi:[1,0]
	v_lshl_add_u64 v[100:101], v[100:101], 0, v[64:65]
	v_cvt_pk_bf16_f32 v88, v92, v93
	v_cvt_pk_bf16_f32 v89, v94, v95
	v_cvt_pk_bf16_f32 v90, v90, v91
	v_cvt_pk_bf16_f32 v91, v102, v103
	global_store_dwordx4 v[100:101], v[88:91], off
	v_pk_mul_f32 v[86:87], v[86:87], v[98:99] op_sel_hi:[1,0]
	v_pk_mul_f32 v[84:85], v[84:85], v[98:99] op_sel_hi:[1,0]
	v_pk_mul_f32 v[88:89], v[82:83], v[98:99] op_sel_hi:[1,0]
	v_pk_mul_f32 v[90:91], v[96:97], v[98:99] op_sel_hi:[1,0]
	v_cvt_pk_bf16_f32 v82, v84, v85
	v_cvt_pk_bf16_f32 v83, v86, v87
	v_cvt_pk_bf16_f32 v84, v90, v91
	v_cvt_pk_bf16_f32 v85, v88, v89
	global_store_dwordx4 v[100:101], v[82:85], off offset:256
	v_add_u32_e32 v92, 48, v136
	v_lshl_add_u32 v93, v92, 5, s18
	ds_read_b128 v[82:85], v93
	ds_read_b128 v[86:89], v93 offset:16
	s_waitcnt lgkmcnt(0)
	v_max_f32_e32 v90, v88, v88
	v_max_f32_e32 v91, v86, v86
	v_max_f32_e32 v90, v91, v90
	v_max3_f32 v94, v82, v84, v90
	v_sub_f32_e32 v82, v82, v94
	v_mul_f32_e32 v82, 0x3fb8aa3b, v82
	v_exp_f32_e32 v90, v82
	v_sub_f32_e32 v82, v84, v94
	v_mul_f32_e32 v82, 0x3fb8aa3b, v82
	v_exp_f32_e32 v91, v82
	v_mov_b32_e32 v84, v83
	v_pk_mul_f32 v[82:83], v[84:85], v[90:91]
	v_sub_f32_e32 v84, v86, v94
	v_mul_f32_e32 v84, 0x3fb8aa3b, v84
	v_exp_f32_e32 v85, v84
	v_sub_f32_e32 v84, v88, v94
	v_mul_f32_e32 v84, 0x3fb8aa3b, v84
	v_exp_f32_e32 v84, v84
	v_mov_b32_e32 v86, v89
	v_add_f32_e32 v82, v82, v83
	v_pk_mul_f32 v[84:85], v[86:87], v[84:85]
	s_nop 0
	v_add_f32_e32 v82, v85, v82
	v_add_f32_e32 v84, v84, v82
	v_add_u32_e32 v82, s55, v93
	ds_read_b64 v[82:83], v82
	s_waitcnt lgkmcnt(0)
	v_sub_f32_e32 v82, v82, v94
	v_mul_f32_e32 v82, 0x3fb8aa3b, v82
	v_exp_f32_e32 v82, v82
	s_nop 0
	v_div_scale_f32 v83, s[20:21], v84, v84, v82
	v_rcp_f32_e32 v85, v83
	s_nop 0
	v_fma_f32 v86, -v83, v85, 1.0
	v_fmac_f32_e32 v85, v86, v85
	v_div_scale_f32 v86, vcc, v82, v84, v82
	v_mul_f32_e32 v87, v86, v85
	v_fma_f32 v88, -v83, v87, v86
	v_fmac_f32_e32 v87, v88, v85
	v_fma_f32 v83, -v83, v87, v86
	v_div_fmas_f32 v83, v83, v85, v87
	v_div_fixup_f32 v82, v83, v84, v82
	v_add_u32_e32 v84, s9, v92
	v_ashrrev_i32_e32 v85, 31, v84
	v_lshlrev_b64 v[84:85], 11, v[84:85]
	v_lshl_add_u64 v[84:85], s[4:5], 0, v[84:85]
	v_lshl_add_u64 v[84:85], v[84:85], 0, s[16:17]
	v_lshl_add_u64 v[84:85], v[84:85], 0, s[44:45]
	v_pk_mul_f32 v[78:79], v[78:79], v[82:83] op_sel_hi:[1,0]
	v_pk_mul_f32 v[76:77], v[76:77], v[82:83] op_sel_hi:[1,0]
	v_pk_mul_f32 v[86:87], v[74:75], v[82:83] op_sel_hi:[1,0]
	v_pk_mul_f32 v[74:75], v[72:73], v[82:83] op_sel_hi:[1,0]
	v_lshl_add_u64 v[84:85], v[84:85], 0, v[64:65]
	v_cvt_pk_bf16_f32 v72, v76, v77
	v_cvt_pk_bf16_f32 v73, v78, v79
	v_cvt_pk_bf16_f32 v74, v74, v75
	v_cvt_pk_bf16_f32 v75, v86, v87
	global_store_dwordx4 v[84:85], v[72:75], off
	v_pk_mul_f32 v[70:71], v[70:71], v[82:83] op_sel_hi:[1,0]
	v_pk_mul_f32 v[68:69], v[68:69], v[82:83] op_sel_hi:[1,0]
	v_pk_mul_f32 v[72:73], v[66:67], v[82:83] op_sel_hi:[1,0]
	v_pk_mul_f32 v[74:75], v[80:81], v[82:83] op_sel_hi:[1,0]
	v_cvt_pk_bf16_f32 v66, v68, v69
	v_cvt_pk_bf16_f32 v67, v70, v71
	v_cvt_pk_bf16_f32 v68, v74, v75
	v_cvt_pk_bf16_f32 v69, v72, v73
	global_store_dwordx4 v[84:85], v[66:69], off offset:256
	v_add_u32_e32 v76, 0x80, v136
	v_lshl_add_u32 v77, v76, 5, s18
	ds_read_b128 v[66:69], v77
	ds_read_b128 v[70:73], v77 offset:16
	s_waitcnt lgkmcnt(0)
	v_max_f32_e32 v74, v72, v72
	v_max_f32_e32 v75, v70, v70
	v_max_f32_e32 v74, v75, v74
	v_max3_f32 v78, v66, v68, v74
	v_sub_f32_e32 v66, v66, v78
	v_mul_f32_e32 v66, 0x3fb8aa3b, v66
	v_exp_f32_e32 v74, v66
	v_sub_f32_e32 v66, v68, v78
	v_mul_f32_e32 v66, 0x3fb8aa3b, v66
	v_exp_f32_e32 v75, v66
	v_mov_b32_e32 v68, v67
	v_pk_mul_f32 v[66:67], v[68:69], v[74:75]
	v_sub_f32_e32 v68, v70, v78
	v_mul_f32_e32 v68, 0x3fb8aa3b, v68
	v_exp_f32_e32 v69, v68
	v_sub_f32_e32 v68, v72, v78
	v_mul_f32_e32 v68, 0x3fb8aa3b, v68
	v_exp_f32_e32 v68, v68
	v_mov_b32_e32 v70, v73
	v_add_f32_e32 v66, v66, v67
	v_pk_mul_f32 v[68:69], v[70:71], v[68:69]
	s_nop 0
	v_add_f32_e32 v66, v69, v66
	v_add_f32_e32 v68, v68, v66
	v_add_u32_e32 v66, s55, v77
	ds_read_b64 v[66:67], v66
	s_waitcnt lgkmcnt(0)
; DI u32x4 pack8(f32x4 a, f32x4 b) { u32x4 w; w.x = cvt_pk_bf16(a[0], a[1]); w.y = cvt_pk_bf16(a[2], a[3]); w.z = cvt_pk_bf16(b[0], b[1]); w.w = cvt_pk_bf16(b[2], b[3]); return w; }
;     DI void operator()(f32x4 (&acc)[2][2][4][2], const Unit& u, int wr, int wc, int fr, int fq, LAS unsigned char* lx) const {
;     ...
;         for (int ai = 0; ai < 2; ++ai)
; #pragma unroll
;             for (int m = 0; m < 4; ++m) {
;                 const int r = ai * HALF + wr * 64 + m * 16 + fr;
;                 const f32x2 a = X[r * 4 + 0], b = X[r * 4 + 1], c = X[r * 4 + 2], d = X[r * 4 + 3];
;                 const float M = fmaxf(fmaxf(a.x, b.x), fmaxf(c.x, d.x));
;                 const float S = a.y * __expf(a.x - M) + b.y * __expf(b.x - M) + c.y * __expf(c.x - M) + d.y * __expf(d.x - M);
;                 const float fac = __expf(X[r * 4 + wc].x - M) / S;
;                 bf16_t* rowp = O + (size_t)(u.pm * BM + r) * ldc + u.z * 256 + wc * 32 + 8 * fq;
; #pragma unroll
;                 for (int bj = 0; bj < 2; ++bj) *(u32x4*)(rowp + bj * HALF) = pack8(acc[ai][bj][m][0] * fac, acc[ai][bj][m][1] * fac);
;                 __builtin_amdgcn_sched_barrier(0);
;             }
	v_sub_f32_e32 v66, v66, v78
	v_mul_f32_e32 v66, 0x3fb8aa3b, v66
	v_exp_f32_e32 v66, v66
	s_nop 0
	v_div_scale_f32 v67, s[20:21], v68, v68, v66
	v_rcp_f32_e32 v69, v67
	s_nop 0
	v_fma_f32 v70, -v67, v69, 1.0
	v_fmac_f32_e32 v69, v70, v69
	v_div_scale_f32 v70, vcc, v66, v68, v66
	v_mul_f32_e32 v71, v70, v69
	v_fma_f32 v72, -v67, v71, v70
	v_fmac_f32_e32 v71, v72, v69
	v_fma_f32 v67, -v67, v71, v70
	v_div_fmas_f32 v67, v67, v69, v71
	v_div_fixup_f32 v66, v67, v68, v66
	v_add_u32_e32 v68, s9, v76
	v_ashrrev_i32_e32 v69, 31, v68
	v_lshlrev_b64 v[68:69], 11, v[68:69]
	v_lshl_add_u64 v[68:69], s[4:5], 0, v[68:69]
	v_lshl_add_u64 v[68:69], v[68:69], 0, s[16:17]
	v_lshl_add_u64 v[68:69], v[68:69], 0, s[44:45]
	v_pk_mul_f32 v[62:63], v[62:63], v[66:67] op_sel_hi:[1,0]
	v_pk_mul_f32 v[60:61], v[60:61], v[66:67] op_sel_hi:[1,0]
	v_pk_mul_f32 v[70:71], v[58:59], v[66:67] op_sel_hi:[1,0]
	v_pk_mul_f32 v[58:59], v[56:57], v[66:67] op_sel_hi:[1,0]
	v_lshl_add_u64 v[68:69], v[68:69], 0, v[64:65]
	v_cvt_pk_bf16_f32 v56, v60, v61
	v_cvt_pk_bf16_f32 v57, v62, v63
	v_cvt_pk_bf16_f32 v58, v58, v59
	v_cvt_pk_bf16_f32 v59, v70, v71
	global_store_dwordx4 v[68:69], v[56:59], off
	v_pk_mul_f32 v[54:55], v[54:55], v[66:67] op_sel_hi:[1,0]
	v_pk_mul_f32 v[52:53], v[52:53], v[66:67] op_sel_hi:[1,0]
	v_pk_mul_f32 v[56:57], v[50:51], v[66:67] op_sel_hi:[1,0]
	v_pk_mul_f32 v[50:51], v[48:49], v[66:67] op_sel_hi:[1,0]
	v_cvt_pk_bf16_f32 v48, v52, v53
	v_cvt_pk_bf16_f32 v49, v54, v55
	v_cvt_pk_bf16_f32 v50, v50, v51
	v_cvt_pk_bf16_f32 v51, v56, v57
	global_store_dwordx4 v[68:69], v[48:51], off offset:256
	v_add_u32_e32 v58, 0x90, v136
	v_lshl_add_u32 v59, v58, 5, s18
	ds_read_b128 v[48:51], v59
	ds_read_b128 v[52:55], v59 offset:16
	s_waitcnt lgkmcnt(0)
	v_max_f32_e32 v56, v54, v54
	v_max_f32_e32 v57, v52, v52
	v_max_f32_e32 v56, v57, v56
	v_max3_f32 v60, v48, v50, v56
	v_sub_f32_e32 v48, v48, v60
	v_mul_f32_e32 v48, 0x3fb8aa3b, v48
	v_exp_f32_e32 v56, v48
	v_sub_f32_e32 v48, v50, v60
	v_mul_f32_e32 v48, 0x3fb8aa3b, v48
	v_exp_f32_e32 v57, v48
	v_mov_b32_e32 v50, v49
	v_pk_mul_f32 v[48:49], v[50:51], v[56:57]
	v_sub_f32_e32 v50, v52, v60
	v_mul_f32_e32 v50, 0x3fb8aa3b, v50
	v_exp_f32_e32 v51, v50
	v_sub_f32_e32 v50, v54, v60
	v_mul_f32_e32 v50, 0x3fb8aa3b, v50
	v_exp_f32_e32 v50, v50
	v_mov_b32_e32 v52, v55
	v_add_f32_e32 v48, v48, v49
	v_pk_mul_f32 v[50:51], v[52:53], v[50:51]
	s_nop 0
	v_add_f32_e32 v48, v51, v48
	v_add_f32_e32 v50, v50, v48
	v_add_u32_e32 v48, s55, v59
	ds_read_b64 v[48:49], v48
	s_waitcnt lgkmcnt(0)
	v_sub_f32_e32 v48, v48, v60
	v_mul_f32_e32 v48, 0x3fb8aa3b, v48
	v_exp_f32_e32 v48, v48
	s_nop 0
	v_div_scale_f32 v49, s[20:21], v50, v50, v48
	v_rcp_f32_e32 v51, v49
	s_nop 0
	v_fma_f32 v52, -v49, v51, 1.0
	v_fmac_f32_e32 v51, v52, v51
	v_div_scale_f32 v52, vcc, v48, v50, v48
	v_mul_f32_e32 v53, v52, v51
	v_fma_f32 v54, -v49, v53, v52
	v_fmac_f32_e32 v53, v54, v51
	v_fma_f32 v49, -v49, v53, v52
	v_div_fmas_f32 v49, v49, v51, v53
	v_div_fixup_f32 v48, v49, v50, v48
	v_add_u32_e32 v50, s9, v58
	v_ashrrev_i32_e32 v51, 31, v50
	v_lshlrev_b64 v[50:51], 11, v[50:51]
	v_lshl_add_u64 v[50:51], s[4:5], 0, v[50:51]
	v_lshl_add_u64 v[50:51], v[50:51], 0, s[16:17]
	v_lshl_add_u64 v[50:51], v[50:51], 0, s[44:45]
	v_pk_mul_f32 v[46:47], v[46:47], v[48:49] op_sel_hi:[1,0]
	v_pk_mul_f32 v[44:45], v[44:45], v[48:49] op_sel_hi:[1,0]
	v_pk_mul_f32 v[52:53], v[42:43], v[48:49] op_sel_hi:[1,0]
	v_pk_mul_f32 v[42:43], v[40:41], v[48:49] op_sel_hi:[1,0]
	v_lshl_add_u64 v[50:51], v[50:51], 0, v[64:65]
	v_cvt_pk_bf16_f32 v40, v44, v45
	v_cvt_pk_bf16_f32 v41, v46, v47
	v_cvt_pk_bf16_f32 v42, v42, v43
	v_cvt_pk_bf16_f32 v43, v52, v53
	global_store_dwordx4 v[50:51], v[40:43], off
	v_pk_mul_f32 v[38:39], v[38:39], v[48:49] op_sel_hi:[1,0]
	v_pk_mul_f32 v[36:37], v[36:37], v[48:49] op_sel_hi:[1,0]
	v_pk_mul_f32 v[40:41], v[34:35], v[48:49] op_sel_hi:[1,0]
	v_pk_mul_f32 v[34:35], v[32:33], v[48:49] op_sel_hi:[1,0]
	v_cvt_pk_bf16_f32 v32, v36, v37
	v_cvt_pk_bf16_f32 v33, v38, v39
	v_cvt_pk_bf16_f32 v34, v34, v35
	v_cvt_pk_bf16_f32 v35, v40, v41
	global_store_dwordx4 v[50:51], v[32:35], off offset:256
	v_add_u32_e32 v42, 0xa0, v136
	v_lshl_add_u32 v43, v42, 5, s18
	ds_read_b128 v[32:35], v43
	ds_read_b128 v[36:39], v43 offset:16
	s_waitcnt lgkmcnt(0)
	v_max_f32_e32 v40, v38, v38
	v_max_f32_e32 v41, v36, v36
	v_max_f32_e32 v40, v41, v40
	v_max3_f32 v44, v32, v34, v40
	v_sub_f32_e32 v32, v32, v44
	v_mul_f32_e32 v32, 0x3fb8aa3b, v32
	v_exp_f32_e32 v40, v32
	v_sub_f32_e32 v32, v34, v44
	v_mul_f32_e32 v32, 0x3fb8aa3b, v32
	v_exp_f32_e32 v41, v32
	v_mov_b32_e32 v34, v33
	v_pk_mul_f32 v[32:33], v[34:35], v[40:41]
	v_sub_f32_e32 v34, v36, v44
	v_mul_f32_e32 v34, 0x3fb8aa3b, v34
	v_exp_f32_e32 v35, v34
	v_sub_f32_e32 v34, v38, v44
	v_mul_f32_e32 v34, 0x3fb8aa3b, v34
	v_exp_f32_e32 v34, v34
	v_mov_b32_e32 v36, v39
	v_add_f32_e32 v32, v32, v33
	v_pk_mul_f32 v[34:35], v[36:37], v[34:35]
	s_nop 0
	v_add_f32_e32 v32, v35, v32
	v_add_f32_e32 v34, v34, v32
	v_add_u32_e32 v32, s55, v43
	ds_read_b64 v[32:33], v32
	s_waitcnt lgkmcnt(0)
; #define LDS_WAIT() asm volatile("s_waitcnt lgkmcnt(0)" ::: "memory")
; DI u32x4 pack8(f32x4 a, f32x4 b) { u32x4 w; w.x = cvt_pk_bf16(a[0], a[1]); w.y = cvt_pk_bf16(a[2], a[3]); w.z = cvt_pk_bf16(b[0], b[1]); w.w = cvt_pk_bf16(b[2], b[3]); return w; }
; #define PG8_BAR __builtin_amdgcn_s_barrier()
;     DI void operator()(f32x4 (&acc)[2][2][4][2], const Unit& u, int wr, int wc, int fr, int fq, LAS unsigned char* lx) const {
;     ...
;         for (int ai = 0; ai < 2; ++ai)
; #pragma unroll
;             for (int m = 0; m < 4; ++m) {
;                 const int r = ai * HALF + wr * 64 + m * 16 + fr;
;                 const f32x2 a = X[r * 4 + 0], b = X[r * 4 + 1], c = X[r * 4 + 2], d = X[r * 4 + 3];
;                 const float M = fmaxf(fmaxf(a.x, b.x), fmaxf(c.x, d.x));
;                 const float S = a.y * __expf(a.x - M) + b.y * __expf(b.x - M) + c.y * __expf(c.x - M) + d.y * __expf(d.x - M);
;                 const float fac = __expf(X[r * 4 + wc].x - M) / S;
;                 bf16_t* rowp = O + (size_t)(u.pm * BM + r) * ldc + u.z * 256 + wc * 32 + 8 * fq;
; #pragma unroll
;                 for (int bj = 0; bj < 2; ++bj) *(u32x4*)(rowp + bj * HALF) = pack8(acc[ai][bj][m][0] * fac, acc[ai][bj][m][1] * fac);
;                 __builtin_amdgcn_sched_barrier(0);
;             }
;         LDS_WAIT(); __builtin_amdgcn_s_barrier(); asm volatile("" ::: "memory");
; template <class Epi, class Sched>
; DI void gemm_phase(int wave_, LAS unsigned char* lds, LAS unsigned char* lx, const GemmP g, const Sched& S, const Epi& E) {
;     ...
;         if (wr == 0) PG8_BAR;
;         E(acc, cur, wr, wc, fr, fq, lx);
;         if (!has_next) break;
; #pragma unroll
;         for (int a = 0; a < 2; ++a)
; #pragma unroll
;             for (int b = 0; b < 2; ++b)
; #pragma unroll
;                 for (int m = 0; m < 4; ++m)
; #pragma unroll
;                     for (int n = 0; n < 2; ++n) acc[a][b][m][n] = (f32x4){0.f, 0.f, 0.f, 0.f};
;         cur = nxt; cA = nA; cB = nB; ++ui;
;         if (wr == 1) PG8_BAR;
	v_sub_f32_e32 v32, v32, v44
	v_mul_f32_e32 v32, 0x3fb8aa3b, v32
	v_exp_f32_e32 v32, v32
	s_nop 0
	v_div_scale_f32 v33, s[20:21], v34, v34, v32
	v_rcp_f32_e32 v35, v33
	s_nop 0
	v_fma_f32 v36, -v33, v35, 1.0
	v_fmac_f32_e32 v35, v36, v35
	v_div_scale_f32 v36, vcc, v32, v34, v32
	v_mul_f32_e32 v37, v36, v35
	v_fma_f32 v38, -v33, v37, v36
	v_fmac_f32_e32 v37, v38, v35
	v_fma_f32 v33, -v33, v37, v36
	v_div_fmas_f32 v33, v33, v35, v37
	v_div_fixup_f32 v32, v33, v34, v32
	v_add_u32_e32 v34, s9, v42
	v_ashrrev_i32_e32 v35, 31, v34
	v_lshlrev_b64 v[34:35], 11, v[34:35]
	v_lshl_add_u64 v[34:35], s[4:5], 0, v[34:35]
	v_lshl_add_u64 v[34:35], v[34:35], 0, s[16:17]
	v_lshl_add_u64 v[34:35], v[34:35], 0, s[44:45]
	v_pk_mul_f32 v[30:31], v[30:31], v[32:33] op_sel_hi:[1,0]
	v_pk_mul_f32 v[28:29], v[28:29], v[32:33] op_sel_hi:[1,0]
	v_pk_mul_f32 v[36:37], v[26:27], v[32:33] op_sel_hi:[1,0]
	v_pk_mul_f32 v[26:27], v[24:25], v[32:33] op_sel_hi:[1,0]
	v_lshl_add_u64 v[34:35], v[34:35], 0, v[64:65]
	v_cvt_pk_bf16_f32 v24, v28, v29
	v_cvt_pk_bf16_f32 v25, v30, v31
	v_cvt_pk_bf16_f32 v26, v26, v27
	v_cvt_pk_bf16_f32 v27, v36, v37
	global_store_dwordx4 v[34:35], v[24:27], off
	v_pk_mul_f32 v[22:23], v[22:23], v[32:33] op_sel_hi:[1,0]
	v_pk_mul_f32 v[20:21], v[20:21], v[32:33] op_sel_hi:[1,0]
	v_pk_mul_f32 v[24:25], v[18:19], v[32:33] op_sel_hi:[1,0]
	v_pk_mul_f32 v[18:19], v[16:17], v[32:33] op_sel_hi:[1,0]
	v_cvt_pk_bf16_f32 v16, v20, v21
	v_cvt_pk_bf16_f32 v17, v22, v23
	v_cvt_pk_bf16_f32 v18, v18, v19
	v_cvt_pk_bf16_f32 v19, v24, v25
	global_store_dwordx4 v[34:35], v[16:19], off offset:256
	v_add_u32_e32 v26, 0xb0, v136
	v_lshl_add_u32 v27, v26, 5, s18
	ds_read_b128 v[16:19], v27
	ds_read_b128 v[20:23], v27 offset:16
	s_waitcnt lgkmcnt(0)
	v_max_f32_e32 v24, v22, v22
	v_max_f32_e32 v25, v20, v20
	v_max_f32_e32 v24, v25, v24
	v_max3_f32 v28, v16, v18, v24
	v_sub_f32_e32 v16, v16, v28
	v_mul_f32_e32 v16, 0x3fb8aa3b, v16
	v_exp_f32_e32 v24, v16
	v_sub_f32_e32 v16, v18, v28
	v_mul_f32_e32 v16, 0x3fb8aa3b, v16
	v_exp_f32_e32 v25, v16
	v_mov_b32_e32 v18, v17
	v_pk_mul_f32 v[16:17], v[18:19], v[24:25]
	v_sub_f32_e32 v18, v20, v28
	v_mul_f32_e32 v18, 0x3fb8aa3b, v18
	v_exp_f32_e32 v19, v18
	v_sub_f32_e32 v18, v22, v28
	v_mul_f32_e32 v18, 0x3fb8aa3b, v18
	v_exp_f32_e32 v18, v18
	v_mov_b32_e32 v20, v23
	v_add_f32_e32 v16, v16, v17
	v_pk_mul_f32 v[18:19], v[20:21], v[18:19]
	s_nop 0
	v_add_f32_e32 v16, v19, v16
	v_add_f32_e32 v18, v18, v16
	v_add_u32_e32 v16, s55, v27
	ds_read_b64 v[16:17], v16
	s_waitcnt lgkmcnt(0)
	v_sub_f32_e32 v16, v16, v28
	v_mul_f32_e32 v16, 0x3fb8aa3b, v16
	v_exp_f32_e32 v16, v16
	s_nop 0
	v_div_scale_f32 v17, s[18:19], v18, v18, v16
	v_rcp_f32_e32 v19, v17
	s_nop 0
	v_fma_f32 v20, -v17, v19, 1.0
	v_fmac_f32_e32 v19, v20, v19
	v_div_scale_f32 v20, vcc, v16, v18, v16
	v_mul_f32_e32 v21, v20, v19
	v_fma_f32 v22, -v17, v21, v20
	v_fmac_f32_e32 v21, v22, v19
	v_fma_f32 v17, -v17, v21, v20
	v_div_fmas_f32 v17, v17, v19, v21
	v_div_fixup_f32 v16, v17, v18, v16
	v_add_u32_e32 v18, s9, v26
	v_ashrrev_i32_e32 v19, 31, v18
	v_lshlrev_b64 v[18:19], 11, v[18:19]
	v_lshl_add_u64 v[18:19], s[4:5], 0, v[18:19]
	v_lshl_add_u64 v[18:19], v[18:19], 0, s[16:17]
	v_lshl_add_u64 v[18:19], v[18:19], 0, s[44:45]
	v_pk_mul_f32 v[14:15], v[14:15], v[16:17] op_sel_hi:[1,0]
	v_pk_mul_f32 v[12:13], v[12:13], v[16:17] op_sel_hi:[1,0]
	v_pk_mul_f32 v[20:21], v[10:11], v[16:17] op_sel_hi:[1,0]
	v_pk_mul_f32 v[10:11], v[8:9], v[16:17] op_sel_hi:[1,0]
	v_lshl_add_u64 v[18:19], v[18:19], 0, v[64:65]
	v_cvt_pk_bf16_f32 v8, v12, v13
	v_cvt_pk_bf16_f32 v9, v14, v15
	v_cvt_pk_bf16_f32 v10, v10, v11
	v_cvt_pk_bf16_f32 v11, v20, v21
	global_store_dwordx4 v[18:19], v[8:11], off
	v_pk_mul_f32 v[6:7], v[6:7], v[16:17] op_sel_hi:[1,0]
	v_pk_mul_f32 v[4:5], v[4:5], v[16:17] op_sel_hi:[1,0]
	v_pk_mul_f32 v[8:9], v[2:3], v[16:17] op_sel_hi:[1,0]
	v_pk_mul_f32 v[2:3], v[0:1], v[16:17] op_sel_hi:[1,0]
	v_cvt_pk_bf16_f32 v0, v4, v5
	v_cvt_pk_bf16_f32 v1, v6, v7
	v_cvt_pk_bf16_f32 v2, v2, v3
	v_cvt_pk_bf16_f32 v3, v8, v9
	global_store_dwordx4 v[18:19], v[0:3], off offset:256
	s_waitcnt lgkmcnt(0)
	s_barrier
	s_andn2_b64 vcc, exec, s[14:15]
	s_mov_b64 s[14:15], -1
	s_cbranch_vccnz .LBB0_1133
	s_andn2_b64 vcc, exec, s[2:3]
	s_cbranch_vccnz .LBB0_1132
	s_barrier
	s_branch .LBB0_1132
.Ltramp_b:
	s_branch .LBB0_1671
.LBB0_1159:
	s_waitcnt vmcnt(0)
	s_barrier
